# gate/up GEMM tile boundary: header waits only for the prefetched K-tiles (vmcnt 8), first two peel waits relaxed (10,16) so epilogue stores drain under the next tile
# speedup vs baseline: 1.0010x; 1.0010x over previous
; #define PG8_STAGE(bufoff, gbase, voff) do { _Pragma("unroll") for (int _i = 0; _i < 2; ++_i) \
;         __builtin_amdgcn_global_load_lds((const unsigned*)((const char*)(gbase) + (voff)[_i]), (PG8_LAS unsigned*)(lds + (bufoff) + ldsw + _i * 8192), 16, 0, 0); } while (0)
; #define PG8_WAIT_V(n) asm volatile("s_waitcnt vmcnt(" #n ")" ::: "memory")
; #define PG8_BAR __builtin_amdgcn_s_barrier()
; template <class Epi, class Sched, bool ALIGN_EPI = false, bool SP2 = false>
; __device__ __forceinline__ void gemm_phase(PG8_LAS unsigned char* lds, const Gemm g, const Sched& S, const Epi& E) {
;     ...
;     for (int i = 0; i < 2; ++i) { int R, C; stage_rc(tid * 16 + i * 8192, R, C); const int Rb = Epi::PERM ? ((R & ~31) + perm32(R & 31)) : R;
;         voffA[i] = (unsigned)(R * K + C) * 2u; voffB[i] = (unsigned)(Rb * K + C) * 2u; }
;     const size_t kstep = (size_t)(BK * 2);
;     const size_t hstep = (size_t)HALF * K * 2;
;     const size_t tstep = 2 * hstep;
;     const unsigned ldsw = (unsigned)wid * 1024u;
;     const int aoff = lds_byte(wr * 64 + fr, fq * 8), boff = lds_byte(wc * 32 + fr, fq * 8);
;     ...
;     const char* cA = (const char*)g.A + (size_t)cur.pm * tstep; const char* cB = (const char*)g.Bt + (size_t)cur.pn * tstep;
;     S.a_ready(cur);
;     if constexpr (SP2) {
;         PG8_STAGE(PG8_SB(0, 0), cB, voffB); PG8_STAGE(PG8_SB(0, 1), cB + hstep, voffB); PG8_STAGE(PG8_SA(0, 0), cA, voffA); PG8_STAGE(PG8_SA(0, 1), cA + hstep, voffA);
;         if (wr == 1) PG8_BAR;
;         PG8_WAIT_V(2); PG8_BAR;
;         PG8_STAGE(PG8_SB(1, 0), cB + kstep, voffB); PG8_STAGE(PG8_SA(1, 0), cA + kstep, voffA); PG8_STAGE(PG8_SB(1, 1), cB + hstep + kstep, voffB);
;         PG8_WAIT_V(6); PG8_BAR;
.LBB0_1097:
	v_lshl_add_u64 v[14:15], s[22:23], 0, v[156:157]
	v_mov_b32_e32 v135, v157
	v_readlane_b32 s14, v254, 14
	s_lshl_b32 s6, s6, 5
	v_lshl_add_u64 v[16:17], s[22:23], 0, v[134:135]
	v_mov_b32_e32 v139, v157
	v_readlane_b32 s15, v254, 15
	s_and_b32 s10, s6, 0x60
	s_add_i32 m0, s87, 0x18000
	v_lshl_add_u64 v[14:15], v[14:15], 0, s[68:69]
	v_lshl_add_u64 v[18:19], s[14:15], 0, v[138:139]
	v_mov_b32_e32 v137, v157
	s_lshl_b32 s8, s5, 13
	s_lshl_b32 s9, s10, 7
	s_waitcnt vmcnt(2)
	s_barrier
	global_load_lds_dwordx4 v[14:15], off
	v_lshl_add_u64 v[14:15], v[16:17], 0, s[68:69]
	s_add_i32 m0, s87, 0x1a000
	s_add_i32 s33, s87, 0x8000
	s_add_i32 s90, s87, 0xa000
	v_lshl_add_u64 v[20:21], s[14:15], 0, v[136:137]
	global_load_lds_dwordx4 v[14:15], off
	v_lshl_add_u64 v[14:15], v[18:19], 0, s[68:69]
	s_mov_b32 m0, s33
	s_add_u32 s6, s22, 0x40080
	global_load_lds_dwordx4 v[14:15], off
	v_lshl_add_u64 v[14:15], v[20:21], 0, s[68:69]
	s_mov_b32 m0, s90
	s_addc_u32 s7, s23, 0
	global_load_lds_dwordx4 v[14:15], off
	s_add_i32 m0, s87, 0x1c000
	v_lshl_add_u64 v[14:15], s[6:7], 0, v[156:157]
	global_load_lds_dwordx4 v[14:15], off
	v_lshl_add_u64 v[14:15], s[6:7], 0, v[134:135]
	s_add_i32 m0, s87, 0x1e000
	v_and_b32_e32 v13, 15, v6
	global_load_lds_dwordx4 v[14:15], off
	v_lshrrev_b32_e32 v14, 1, v6
	v_and_b32_e32 v14, 24, v14
	v_lshlrev_b32_e32 v15, 1, v14
	v_lshlrev_b32_e32 v6, 2, v6
	v_lshl_or_b32 v152, s5, 6, v13
	v_lshl_or_b32 v13, v13, 6, v15
	v_and_b32_e32 v6, 32, v6
	v_bitop3_b32 v15, v13, s8, v6 bitop3:0xde
	v_bitop3_b32 v153, v13, s9, v6 bitop3:0xde
	v_lshlrev_b32_e32 v6, 14, v11
	v_and_b32_e32 v6, 0xffff8000, v6
	v_lshl_add_u32 v6, v10, 11, v6
	v_and_b32_e32 v10, 1, v11
	v_lshl_or_b32 v6, v10, 6, v6
	v_lshl_add_u32 v140, v12, 1, v6
	v_lshlrev_b32_e32 v6, 14, v7
	v_and_b32_e32 v6, 0xffff8000, v6
	s_waitcnt vmcnt(6)
	s_cmpk_lt_u32 s4, 0x100
	v_lshl_add_u32 v6, v8, 11, v6
	v_and_b32_e32 v7, 1, v7
	v_readlane_b32 s4, v254, 12
	v_lshl_or_b32 v6, v7, 6, v6
	v_readlane_b32 s5, v254, 13
	s_cselect_b64 s[8:9], -1, 0
	v_or_b32_e32 v155, s10, v14
	v_mov_b32_e32 v141, v157
	v_lshl_add_u32 v142, v9, 1, v6
	v_mov_b32_e32 v143, v157
	s_mov_b32 s91, 0
	v_add_u32_e32 v162, 0, v15
	v_readlane_b32 s80, v254, 7
	s_mov_b32 s24, s4
	s_mov_b64 s[4:5], s[14:15]
	s_barrier
	s_waitcnt vmcnt(0)
	s_nop 0
	s_branch .LBB0_1100

; template <class Epi, class Sched, bool ALIGN_EPI = false, bool SP2 = false>
; __device__ __forceinline__ void gemm_phase(PG8_LAS unsigned char* lds, const Gemm g, const Sched& S, const Epi& E) {
;     ...
;     for (;;) {
;         const bool has_next = S.next(ui + 1, nxt);
;         const char* nA = has_next ? (const char*)g.A + (size_t)nxt.pm * tstep : cA; const char* nB = has_next ? (const char*)g.Bt + (size_t)nxt.pn * tstep : cB;
;         for (int t = 0; t < nt; t += 2) {
;             const bool last = (t == nt - 2);
;             const char* a1 = cA + (size_t)(t + 1) * kstep;
;             const char* a2 = last ? nA : cA + (size_t)(t + 2) * kstep; const char* b2 = last ? nB : cB + (size_t)(t + 2) * kstep;
;             const char* a3 = a2 + kstep; const char* b3 = b2 + kstep;
;             if (last && has_next) S.a_ready(nxt);
;             if (last) E.pre(cur, wr, fr, rsv);
.LBB0_1102:
	s_ashr_i32 s13, s12, 31
	s_lshl_b64 s[14:15], s[12:13], 19
	s_add_u32 s14, s74, s14
	s_addc_u32 s15, s75, s15
	s_and_b64 s[20:21], s[6:7], exec
	s_cselect_b32 s13, s15, s5
	s_cselect_b32 s36, s14, s4
	s_ashr_i32 s11, s10, 31
	s_lshl_b64 s[20:21], s[10:11], 19
	s_add_u32 s20, s16, s20
	s_addc_u32 s21, s78, s21
	s_and_b64 s[38:39], s[6:7], exec
	s_cselect_b32 s11, s21, s23
	s_cselect_b32 s37, s20, s22
	s_add_u32 s4, s4, 0x40080
	v_lshl_add_u32 v144, s24, 8, v152
	s_addc_u32 s5, s5, 0
	v_ashrrev_i32_e32 v145, 31, v144
	s_add_u32 s38, s22, 0x100
	v_lshl_add_u64 v[146:147], v[144:145], 2, s[52:53]
	s_addc_u32 s39, s23, 0
	s_mov_b32 s40, -2
	s_waitcnt vmcnt(8)
	s_branch .LBB0_1104
; #define PG8_STAGE(bufoff, gbase, voff) do { _Pragma("unroll") for (int _i = 0; _i < 2; ++_i) \
;         __builtin_amdgcn_global_load_lds((const unsigned*)((const char*)(gbase) + (voff)[_i]), (PG8_LAS unsigned*)(lds + (bufoff) + ldsw + _i * 8192), 16, 0, 0); } while (0)
; #define PG8_LDA(dst, b, h) do { _Pragma("unroll") for (int m = 0; m < 4; ++m) _Pragma("unroll") for (int k = 0; k < 2; ++k) dst[m][k] = *(const PG8_LAS bf16x8*)(lds + PG8_SA(b, h) + aoff + m * 2048 + k * 1024); } while (0)
; #define PG8_LDB(dst, b, h) do { _Pragma("unroll") for (int n = 0; n < 2; ++n) _Pragma("unroll") for (int k = 0; k < 2; ++k) dst[n][k] = *(const PG8_LAS bf16x8*)(lds + PG8_SB(b, h) + boff + n * 2048 + k * 1024); } while (0)
; #define PG8_MMA(ai, bj, At, Bt) do { __builtin_amdgcn_s_setprio(1); _Pragma("unroll") for (int m = 0; m < 4; ++m) _Pragma("unroll") for (int n = 0; n < 2; ++n) _Pragma("unroll") for (int k = 0; k < 2; ++k) \
;         acc[ai][bj][m][n] = __builtin_amdgcn_mfma_f32_16x16x32_bf16(Bt[n][k], At[m][k], acc[ai][bj][m][n], 0, 0, 0); __builtin_amdgcn_s_setprio(0); } while (0)
; #define PG8_WAIT_V(n) asm volatile("s_waitcnt vmcnt(" #n ")" ::: "memory")
; #define PG8_BAR __builtin_amdgcn_s_barrier()
; template <class Epi, class Sched, bool ALIGN_EPI = false, bool SP2 = false>
; __device__ __forceinline__ void gemm_phase(PG8_LAS unsigned char* lds, const Gemm g, const Sched& S, const Epi& E) {
;     ...
;             const bool last = (t == nt - 2);
;             const char* a1 = cA + (size_t)(t + 1) * kstep;
;             const char* a2 = last ? nA : cA + (size_t)(t + 2) * kstep; const char* b2 = last ? nB : cB + (size_t)(t + 2) * kstep;
;             const char* a3 = a2 + kstep; const char* b3 = b2 + kstep;
;             if (last && has_next) S.a_ready(nxt);
;             if (last) E.pre(cur, wr, fr, rsv);
;             if constexpr (SP2) {
;             PG8_LDB(B0, 0, 0); PG8_LDB(B1, 0, 1); PG8_SCHED; PG8_LDA(At, 0, 0); PG8_STAGE(PG8_SA(1, 1), a1 + hstep, voffA);
;             PG8_WAIT_V(8); PG8_WAIT_L(0); PG8_BAR; PG8_MMA(0, 0, At, B0); PG8_MMA(0, 1, At, B1); PG8_BAR; PG8_SCHED;
;             PG8_LDA(At, 0, 1); PG8_STAGE(PG8_SB(0, 0), b2, voffB); PG8_STAGE(PG8_SB(0, 1), b2 + hstep, voffB); PG8_STAGE(PG8_SA(0, 0), a2, voffA);
;             PG8_WAIT_V(8); PG8_WAIT_L(0); PG8_BAR; PG8_MMA(1, 0, At, B0); PG8_MMA(1, 1, At, B1); PG8_BAR; PG8_SCHED;
.LpeelC:
	s_add_u32 s24, s4, 0xfffc0080
	s_addc_u32 s25, s5, -1
	s_and_b64 s[22:23], s[22:23], exec
	s_cselect_b32 s25, s13, s25
	s_cselect_b32 s24, s36, s24
	s_cselect_b32 s23, s11, s39
	s_cselect_b32 s22, s37, s38
	s_add_i32 s41, 0, 0x10000
	v_add_u32_e32 v145, s41, v153
	s_add_i32 s46, 0, 0x14000
	ds_read_b128 v[148:151], v145
	ds_read_b128 v[172:175], v145 offset:1024
	ds_read_b128 v[176:179], v145 offset:2048
	ds_read_b128 v[180:183], v145 offset:3072
	v_add_u32_e32 v145, s46, v153
	ds_read_b128 v[184:187], v145
	ds_read_b128 v[188:191], v145 offset:1024
	ds_read_b128 v[192:195], v145 offset:2048
	ds_read_b128 v[196:199], v145 offset:3072
	v_lshl_add_u64 v[220:221], s[4:5], 0, v[140:141]
	s_add_i32 m0, s87, 0xc000
	ds_read_b128 v[200:203], v162
	ds_read_b128 v[204:207], v162 offset:1024
	ds_read_b128 v[208:211], v162 offset:2048
	ds_read_b128 v[212:215], v162 offset:3072
	ds_read_b128 v[216:219], v162 offset:4096
	ds_read_b128 v[236:239], v162 offset:5120
	ds_read_b128 v[240:243], v162 offset:6144
	ds_read_b128 v[244:247], v162 offset:7168
	global_load_lds_dwordx4 v[220:221], off
	v_lshl_add_u64 v[220:221], s[4:5], 0, v[142:143]
	s_add_i32 m0, s87, 0xe000
	s_nop 0
	global_load_lds_dwordx4 v[220:221], off
	s_waitcnt vmcnt(10)
	s_waitcnt lgkmcnt(0)
	s_barrier
	s_setprio 1
	s_waitcnt lgkmcnt(0)
	v_mfma_f32_16x16x32_bf16 v[130:133], v[148:151], v[200:203], 0
	v_mfma_f32_16x16x32_bf16 v[126:129], v[176:179], v[200:203], 0
	v_mfma_f32_16x16x32_bf16 v[114:117], v[148:151], v[208:211], 0
	v_mfma_f32_16x16x32_bf16 v[110:113], v[176:179], v[208:211], 0
	v_mfma_f32_16x16x32_bf16 v[98:101], v[148:151], v[216:219], 0
	v_mfma_f32_16x16x32_bf16 v[94:97], v[176:179], v[216:219], 0
	v_mfma_f32_16x16x32_bf16 v[82:85], v[148:151], v[240:243], 0
	v_mfma_f32_16x16x32_bf16 v[78:81], v[176:179], v[240:243], 0
	v_mfma_f32_16x16x32_bf16 v[130:133], v[172:175], v[204:207], v[130:133]
	v_mfma_f32_16x16x32_bf16 v[126:129], v[180:183], v[204:207], v[126:129]
	v_mfma_f32_16x16x32_bf16 v[114:117], v[172:175], v[212:215], v[114:117]
	v_mfma_f32_16x16x32_bf16 v[110:113], v[180:183], v[212:215], v[110:113]
	v_mfma_f32_16x16x32_bf16 v[98:101], v[172:175], v[236:239], v[98:101]
	v_mfma_f32_16x16x32_bf16 v[94:97], v[180:183], v[236:239], v[94:97]
	v_mfma_f32_16x16x32_bf16 v[82:85], v[172:175], v[244:247], v[82:85]
	v_mfma_f32_16x16x32_bf16 v[78:81], v[180:183], v[244:247], v[78:81]
	s_setprio 0
	s_setprio 1
	v_mfma_f32_16x16x32_bf16 v[122:125], v[184:187], v[200:203], 0
	v_mfma_f32_16x16x32_bf16 v[118:121], v[192:195], v[200:203], 0
	v_mfma_f32_16x16x32_bf16 v[106:109], v[184:187], v[208:211], 0
	v_mfma_f32_16x16x32_bf16 v[102:105], v[192:195], v[208:211], 0
	v_mfma_f32_16x16x32_bf16 v[90:93], v[184:187], v[216:219], 0
	v_mfma_f32_16x16x32_bf16 v[86:89], v[192:195], v[216:219], 0
	v_mfma_f32_16x16x32_bf16 v[74:77], v[184:187], v[240:243], 0
	v_mfma_f32_16x16x32_bf16 v[70:73], v[192:195], v[240:243], 0
	v_mfma_f32_16x16x32_bf16 v[122:125], v[188:191], v[204:207], v[122:125]
	v_mfma_f32_16x16x32_bf16 v[118:121], v[196:199], v[204:207], v[118:121]
	v_mfma_f32_16x16x32_bf16 v[106:109], v[188:191], v[212:215], v[106:109]
	v_mfma_f32_16x16x32_bf16 v[102:105], v[196:199], v[212:215], v[102:105]
	v_mfma_f32_16x16x32_bf16 v[90:93], v[188:191], v[236:239], v[90:93]
	v_mfma_f32_16x16x32_bf16 v[86:89], v[196:199], v[236:239], v[86:89]
	v_mfma_f32_16x16x32_bf16 v[74:77], v[188:191], v[244:247], v[74:77]
	v_mfma_f32_16x16x32_bf16 v[70:73], v[196:199], v[244:247], v[70:73]
	s_setprio 0
	s_barrier
	s_add_i32 s41, s41, s79
	v_lshl_add_u64 v[220:221], s[22:23], 0, v[156:157]
	s_mov_b32 m0, s41
	ds_read_b128 v[200:203], v162 offset:16384
	ds_read_b128 v[204:207], v162 offset:17408
	ds_read_b128 v[208:211], v162 offset:18432
	ds_read_b128 v[212:215], v162 offset:19456
	ds_read_b128 v[216:219], v162 offset:20480
	ds_read_b128 v[236:239], v162 offset:21504
	ds_read_b128 v[240:243], v162 offset:22528
	ds_read_b128 v[244:247], v162 offset:23552
	global_load_lds_dwordx4 v[220:221], off
	s_add_i32 m0, s41, 0x2000
	s_add_u32 s44, s22, 0x40000
	v_lshl_add_u64 v[222:223], s[22:23], 0, v[134:135]
	s_addc_u32 s45, s23, 0
	s_add_i32 s41, s46, s79
	global_load_lds_dwordx4 v[222:223], off
	v_lshl_add_u64 v[226:227], s[44:45], 0, v[156:157]
	s_mov_b32 m0, s41
	v_lshl_add_u64 v[248:249], s[24:25], 0, v[136:137]
	global_load_lds_dwordx4 v[226:227], off
	v_lshl_add_u64 v[226:227], s[44:45], 0, v[134:135]
	s_add_i32 m0, s41, 0x2000
	s_nop 0
	global_load_lds_dwordx4 v[226:227], off
	v_lshl_add_u64 v[226:227], s[24:25], 0, v[138:139]
	s_mov_b32 m0, s87
	s_nop 0
	global_load_lds_dwordx4 v[226:227], off
	s_mov_b32 m0, s19
	s_nop 0
	global_load_lds_dwordx4 v[248:249], off
	s_waitcnt vmcnt(16)
	s_waitcnt lgkmcnt(0)
	s_barrier
	s_setprio 1
	s_waitcnt lgkmcnt(0)
	v_mfma_f32_16x16x32_bf16 v[66:69], v[148:151], v[200:203], 0
	v_mfma_f32_16x16x32_bf16 v[62:65], v[176:179], v[200:203], 0
	v_mfma_f32_16x16x32_bf16 v[50:53], v[148:151], v[208:211], 0
	v_mfma_f32_16x16x32_bf16 v[46:49], v[176:179], v[208:211], 0
	v_mfma_f32_16x16x32_bf16 v[34:37], v[148:151], v[216:219], 0
	v_mfma_f32_16x16x32_bf16 v[30:33], v[176:179], v[216:219], 0
	v_mfma_f32_16x16x32_bf16 v[18:21], v[148:151], v[240:243], 0
	v_mfma_f32_16x16x32_bf16 v[14:17], v[176:179], v[240:243], 0
	v_mfma_f32_16x16x32_bf16 v[66:69], v[172:175], v[204:207], v[66:69]
	v_mfma_f32_16x16x32_bf16 v[62:65], v[180:183], v[204:207], v[62:65]
	v_mfma_f32_16x16x32_bf16 v[50:53], v[172:175], v[212:215], v[50:53]
	v_mfma_f32_16x16x32_bf16 v[46:49], v[180:183], v[212:215], v[46:49]
	v_mfma_f32_16x16x32_bf16 v[34:37], v[172:175], v[236:239], v[34:37]
	v_mfma_f32_16x16x32_bf16 v[30:33], v[180:183], v[236:239], v[30:33]
	v_mfma_f32_16x16x32_bf16 v[18:21], v[172:175], v[244:247], v[18:21]
	v_mfma_f32_16x16x32_bf16 v[14:17], v[180:183], v[244:247], v[14:17]
	s_setprio 0
	s_setprio 1
	v_mfma_f32_16x16x32_bf16 v[58:61], v[184:187], v[200:203], 0
	v_mfma_f32_16x16x32_bf16 v[54:57], v[192:195], v[200:203], 0
	v_mfma_f32_16x16x32_bf16 v[42:45], v[184:187], v[208:211], 0
	v_mfma_f32_16x16x32_bf16 v[38:41], v[192:195], v[208:211], 0
	v_mfma_f32_16x16x32_bf16 v[26:29], v[184:187], v[216:219], 0
	v_mfma_f32_16x16x32_bf16 v[22:25], v[192:195], v[216:219], 0
	v_mfma_f32_16x16x32_bf16 v[10:13], v[184:187], v[240:243], 0
	v_mfma_f32_16x16x32_bf16 v[6:9], v[192:195], v[240:243], 0
	v_mfma_f32_16x16x32_bf16 v[58:61], v[188:191], v[204:207], v[58:61]
	v_mfma_f32_16x16x32_bf16 v[54:57], v[196:199], v[204:207], v[54:57]
	v_mfma_f32_16x16x32_bf16 v[42:45], v[188:191], v[212:215], v[42:45]
	v_mfma_f32_16x16x32_bf16 v[38:41], v[196:199], v[212:215], v[38:41]
	v_mfma_f32_16x16x32_bf16 v[26:29], v[188:191], v[236:239], v[26:29]
	v_mfma_f32_16x16x32_bf16 v[22:25], v[196:199], v[236:239], v[22:25]
	v_mfma_f32_16x16x32_bf16 v[10:13], v[188:191], v[244:247], v[10:13]
	v_mfma_f32_16x16x32_bf16 v[6:9], v[196:199], v[244:247], v[6:9]
	s_setprio 0
	s_barrier
	s_branch .LpeelC_mid
